# P3 pre-loop scan block loads batched; P4 loop: edge-only lookups moved to edge path, loop-invariant LDS addresses kept in registers
# speedup vs baseline: 1.0086x; 1.0033x over previous
.LBB0_309:
	v_writelane_b32 v250, s97, 9
	v_writelane_b32 v250, s66, 6
	s_andn2_b64 vcc, exec, s[0:1]
	s_nop 0
	v_writelane_b32 v250, s67, 7
	v_writelane_b32 v250, s95, 8
	s_cbranch_vccnz .LBB0_460
	v_mbcnt_lo_u32_b32 v30, -1, 0
	v_mbcnt_hi_u32_b32 v36, -1, v30
	v_and_b32_e32 v31, 64, v36
	v_xor_b32_e32 v30, 1, v36
	v_add_u32_e32 v32, 64, v31
	v_cmp_lt_i32_e32 vcc, v30, v32
	s_movk_i32 s0, 0x27f
	s_add_i32 s3, 0, 0x4400
	v_cndmask_b32_e32 v37, v36, v30, vcc
	v_xor_b32_e32 v30, 2, v36
	v_cmp_lt_i32_e32 vcc, v30, v32
	s_cmp_lt_u32 s38, 64
	v_lshrrev_b32_e32 v56, 4, v1
	v_cndmask_b32_e32 v38, v36, v30, vcc
	v_xor_b32_e32 v30, 4, v36
	v_cmp_lt_i32_e32 vcc, v30, v32
	v_lshlrev_b32_e32 v58, 2, v56
	v_lshlrev_b32_e32 v86, 3, v0
	v_cndmask_b32_e32 v39, v36, v30, vcc
	v_xor_b32_e32 v30, 8, v36
	v_cmp_lt_i32_e32 vcc, v30, v32
	v_and_b32_e32 v57, 56, v86
	v_mov_b32_e32 v66, 0xffff
	v_cndmask_b32_e32 v40, v36, v30, vcc
	v_add_u32_e32 v30, -1, v36
	v_cmp_lt_i32_e32 vcc, v30, v31
	v_mov_b32_e32 v67, 0xffff0000
	v_or_b32_e32 v63, 2, v57
	v_cndmask_b32_e32 v41, v30, v36, vcc
	v_add_u32_e32 v30, -2, v36
	v_cmp_lt_i32_e32 vcc, v30, v31
	v_or_b32_e32 v65, 4, v57
	v_or_b32_e32 v80, 6, v57
	v_cndmask_b32_e32 v42, v30, v36, vcc
	v_add_u32_e32 v30, -4, v36
	v_cmp_lt_i32_e32 vcc, v30, v31
	v_lshlrev_b32_e32 v90, 2, v1
	v_lshrrev_b32_e32 v85, 2, v0
	v_cndmask_b32_e32 v43, v30, v36, vcc
	v_add_u32_e32 v30, -8, v36
	v_cmp_lt_i32_e32 vcc, v30, v31
	v_and_b32_e32 v85, 0x78, v85
	v_lshlrev_b32_e32 v146, 4, v0
	v_cndmask_b32_e32 v44, v30, v36, vcc
	v_add_u32_e32 v30, -16, v36
	v_cmp_lt_i32_e32 vcc, v30, v31
	v_lshlrev_b32_e32 v158, 2, v37
	v_mov_b32_e32 v37, 0x80
	v_cndmask_b32_e32 v45, v30, v36, vcc
	v_subrev_u32_e32 v30, 32, v36
	v_cmp_lt_i32_e32 vcc, v30, v31
	v_mov_b32_e32 v31, 0xfffffb80
	v_mov_b32_e32 v89, s3
	v_cndmask_b32_e32 v46, v30, v36, vcc
	v_and_b32_e32 v30, 63, v36
	v_cmp_ne_u32_e32 vcc, 63, v30
	v_lshl_or_b32 v173, v36, 2, v37
	v_mov_b32_e32 v37, 0x2000
	v_addc_co_u32_e32 v47, vcc, 0, v36, vcc
	v_cmp_gt_u32_e32 vcc, 62, v30
	v_lshlrev_b32_e32 v163, 2, v42
	v_lshlrev_b32_e32 v166, 2, v45
	v_cndmask_b32_e64 v48, 0, 2, vcc
	v_cmp_gt_u32_e32 vcc, 60, v30
	v_add_lshl_u32 v169, v48, v36, 2
	v_bfe_u32 v45, v0, 4, 1
	v_cndmask_b32_e64 v49, 0, 4, vcc
	v_cmp_gt_u32_e32 vcc, 56, v30
	v_add_lshl_u32 v170, v49, v36, 2
	v_lshlrev_b32_e32 v165, 2, v44
	v_cndmask_b32_e64 v50, 0, 8, vcc
	v_cmp_gt_u32_e32 vcc, 48, v30
	v_mov_b32_e32 v30, 0xba00
	v_add_lshl_u32 v171, v50, v36, 2
	v_cndmask_b32_e64 v51, 0, 16, vcc
	v_cmp_lt_u32_e32 vcc, s0, v0
	s_movk_i32 s0, 0x7f
	v_add_lshl_u32 v172, v51, v36, 2
	v_cndmask_b32_e32 v52, 0, v30, vcc
	v_cndmask_b32_e32 v53, 0, v31, vcc
	v_cmp_lt_u32_e32 vcc, s0, v0
	s_cselect_b64 s[0:1], -1, 0
	v_writelane_b32 v250, s0, 10
	v_cndmask_b32_e32 v54, 0, v30, vcc
	v_and_b32_e32 v30, 15, v0
	v_writelane_b32 v250, s1, 11
	s_add_u32 s0, s74, 0xb4000
	s_addc_u32 s1, s75, 0
	v_writelane_b32 v250, s0, 12
	s_bfe_u32 s33, s38, 0x20006
	s_lshl_b32 s41, s33, 4
	v_writelane_b32 v250, s1, 13
	s_lshr_b32 s0, s38, 8
	s_mul_i32 s1, s0, 0xba00
	s_add_i32 s39, s1, 0
	s_add_i32 s40, s39, 0x8c00
	s_mul_i32 s1, s33, 0x500
	s_mul_i32 s0, s0, 0xffff4700
	s_add_i32 s42, s39, s0
	s_add_i32 s47, s40, s1
	s_cmpk_gt_u32 s38, 0xff
	s_cselect_b64 s[0:1], -1, 0
	v_or_b32_e32 v32, s41, v58
	v_writelane_b32 v250, s0, 14
	s_cmpk_lt_u32 s38, 0x100
	v_cmp_gt_u32_e64 s[4:5], v30, v32
	v_writelane_b32 v250, s1, 15
	s_cselect_b64 s[0:1], -1, 0
	s_xor_b64 s[6:7], s[0:1], s[4:5]
	v_writelane_b32 v250, s6, 16
	v_or_b32_e32 v59, 1, v32
	v_or_b32_e32 v68, 2, v32
	v_writelane_b32 v250, s7, 17
	v_cmp_gt_u32_e64 s[6:7], v30, v59
	s_xor_b64 s[8:9], s[0:1], s[6:7]
	v_writelane_b32 v250, s8, 18
	v_or_b32_e32 v69, 3, v32
	v_or_b32_e32 v35, 16, v30
	v_writelane_b32 v250, s9, 19
	v_cmp_gt_u32_e64 s[8:9], v30, v68
	s_xor_b64 s[10:11], s[0:1], s[8:9]
	v_writelane_b32 v250, s10, 20
	v_cndmask_b32_e32 v55, 0, v31, vcc
	s_lshl_b32 s2, s33, 5
	v_writelane_b32 v250, s11, 21
	v_cmp_gt_u32_e64 s[10:11], v30, v69
	s_xor_b64 s[12:13], s[0:1], s[10:11]
	v_writelane_b32 v250, s12, 22
	v_cmp_eq_u32_e32 vcc, 1, v1
	s_add_i32 s43, s39, s2
	v_writelane_b32 v250, s13, 23
	v_cmp_gt_u32_e64 s[12:13], v35, v32
	s_xor_b64 s[14:15], s[0:1], s[12:13]
	v_writelane_b32 v250, s14, 24
	s_add_i32 s44, 0, 0x21a00
	v_cndmask_b32_e64 v71, 0, 1.0, vcc
	v_writelane_b32 v250, s15, 25
	v_cmp_gt_u32_e64 s[14:15], v35, v59
	s_xor_b64 s[16:17], s[0:1], s[14:15]
	v_writelane_b32 v250, s16, 26
	v_cmp_eq_u32_e32 vcc, 2, v1
	v_or_b32_e32 v34, 32, v30
	v_writelane_b32 v250, s17, 27
	v_cmp_gt_u32_e64 s[16:17], v35, v68
	s_xor_b64 s[18:19], s[0:1], s[16:17]
	v_writelane_b32 v250, s18, 28
	v_cndmask_b32_e64 v70, 0, 1.0, vcc
	v_cmp_eq_u32_e32 vcc, 3, v1
	v_writelane_b32 v250, s19, 29
	v_cmp_gt_u32_e64 s[18:19], v35, v69
	s_xor_b64 s[20:21], s[0:1], s[18:19]
	v_writelane_b32 v250, s20, 30
	s_cmp_eq_u32 s33, 1
	v_cndmask_b32_e64 v87, 0, 1.0, vcc
	v_writelane_b32 v250, s21, 31
	s_cselect_b64 s[20:21], -1, 0
	v_cmp_eq_u32_e32 vcc, 4, v1
	v_writelane_b32 v250, s20, 32
	v_cmp_gt_u32_e64 s[26:27], v34, v69
	v_cndmask_b32_e64 v73, 0, 1.0, vcc
	v_cmp_eq_u32_e32 vcc, 5, v1
	v_writelane_b32 v250, s21, 33
	v_cmp_gt_u32_e64 s[20:21], v34, v32
	v_cndmask_b32_e64 v72, 0, 1.0, vcc
	v_cmp_eq_u32_e32 vcc, 6, v1
	s_xor_b64 s[22:23], s[0:1], s[20:21]
	v_writelane_b32 v250, s22, 34
	v_cndmask_b32_e64 v113, 0, 1.0, vcc
	v_cmp_eq_u32_e32 vcc, 7, v1
	v_writelane_b32 v250, s23, 35
	v_cmp_gt_u32_e64 s[22:23], v34, v59
	v_cndmask_b32_e64 v117, 0, 1.0, vcc
	v_cmp_eq_u32_e32 vcc, 8, v1
	s_xor_b64 s[24:25], s[0:1], s[22:23]
	v_writelane_b32 v250, s24, 36
	v_cndmask_b32_e64 v75, 0, 1.0, vcc
	v_cmp_eq_u32_e32 vcc, 9, v1
	v_writelane_b32 v250, s25, 37
	v_cmp_gt_u32_e64 s[24:25], v34, v68
	v_cndmask_b32_e64 v74, 0, 1.0, vcc
	v_cmp_eq_u32_e32 vcc, 10, v1
	v_or_b32_e32 v33, 48, v30
	s_xor_b64 s[56:57], s[0:1], s[24:25]
	v_cndmask_b32_e64 v144, 0, 1.0, vcc
	v_cmp_eq_u32_e32 vcc, 11, v1
	s_xor_b64 s[58:59], s[0:1], s[26:27]
	s_cmp_eq_u32 s33, 2
	v_cndmask_b32_e64 v145, 0, 1.0, vcc
	v_cmp_eq_u32_e32 vcc, 12, v1
	v_cmp_gt_u32_e64 s[28:29], v33, v32
	v_cmp_gt_u32_e64 s[30:31], v33, v59
	v_cndmask_b32_e64 v77, 0, 1.0, vcc
	v_cmp_eq_u32_e32 vcc, 13, v1
	v_cmp_gt_u32_e64 s[34:35], v33, v68
	v_cmp_gt_u32_e64 s[36:37], v33, v69
	v_cndmask_b32_e64 v79, 0, 1.0, vcc
	v_cmp_eq_u32_e32 vcc, 14, v1
	v_lshrrev_b32_e32 v31, 3, v0
	s_cselect_b64 s[60:61], -1, 0
	s_xor_b64 s[62:63], s[0:1], s[28:29]
	s_xor_b64 s[64:65], s[0:1], s[30:31]
	s_xor_b64 s[90:91], s[0:1], s[34:35]
	v_cndmask_b32_e64 v78, 0, 1.0, vcc
	v_cmp_eq_u32_e32 vcc, 15, v1
	s_xor_b64 s[94:95], s[0:1], s[36:37]
	s_mul_i32 s45, s33, 0x300
	v_cndmask_b32_e64 v76, 0, 1.0, vcc
	v_cmp_gt_u32_e32 vcc, v57, v31
	s_cmp_eq_u32 s33, 3
	s_cselect_b64 s[96:97], -1, 0
	v_cndmask_b32_e64 v60, v66, 0, vcc
	v_cmp_lt_u32_e32 vcc, v57, v31
	s_add_i32 s45, s40, s45
	s_add_u32 s84, s74, 0x39c4000
	v_cndmask_b32_e32 v61, 0, v67, vcc
	v_cmp_gt_u32_e32 vcc, v63, v31
	s_addc_u32 s85, s75, 0
	s_bfe_u32 s46, s38, 0x10006
	v_cndmask_b32_e64 v62, v66, 0, vcc
	v_cmp_lt_u32_e32 vcc, v63, v31
	v_readlane_b32 s54, v250, 6
	s_bitcmp1_b32 s38, 6
	v_cndmask_b32_e32 v63, 0, v67, vcc
	v_cmp_gt_u32_e32 vcc, v65, v31
	v_readlane_b32 s55, v250, 7
	s_cselect_b64 s[86:87], -1, 0
	v_cndmask_b32_e64 v64, v66, 0, vcc
	v_cmp_lt_u32_e32 vcc, v65, v31
	s_ashr_i32 s55, s54, 31
	s_lshl_b64 s[0:1], s[54:55], 10
	v_cndmask_b32_e32 v65, 0, v67, vcc
	v_cmp_gt_u32_e32 vcc, v80, v31
	v_mov_b32_e32 v81, s1
	v_lshlrev_b32_e32 v84, 10, v30
	v_cndmask_b32_e64 v66, v66, 0, vcc
	v_cmp_lt_u32_e32 vcc, v80, v31
	v_or_b32_e32 v80, s0, v90
	s_lshl_b64 s[0:1], s[54:55], 14
	v_or3_b32 v84, s0, v84, v85
	v_mov_b32_e32 v85, s1
	v_or_b32_e32 v82, s0, v146
	v_mov_b32_e32 v83, s1
	v_lshl_add_u64 v[84:85], s[72:73], 0, v[84:85]
	s_mov_b64 s[0:1], 0x2000200
	v_lshl_add_u64 v[84:85], v[84:85], 0, s[0:1]
	v_or_b32_e32 v92, s41, v30
	s_movk_i32 s0, 0x110
	v_lshlrev_b32_e32 v151, 7, v59
	v_lshlrev_b32_e32 v59, 6, v0
	v_mad_u32_u24 v88, v92, s0, 0
	v_and_b32_e32 v59, 0x400, v59
	s_movk_i32 s0, 0x78
	v_and_or_b32 v154, v86, s0, v59
	v_mov_b32_e32 v86, s40
	s_movk_i32 s0, 0x50
	v_writelane_b32 v250, s47, 38
	v_mov_b32_e32 v59, s47
	v_lshl_or_b32 v98, s46, 4, v30
	v_mad_u32_u24 v59, v30, s0, v59
	v_mad_u32_u24 v157, v98, s0, v86
	v_readlane_b32 s0, v250, 9
	s_lshl_b32 s0, s0, 3
	s_and_b32 s0, s0, 16
	v_or_b32_e32 v99, s0, v58
	s_or_b32 s0, s0, 32
	v_or_b32_e32 v100, s0, v30
	v_or_b32_e32 v58, s0, v58
	v_sub_co_u32_e64 v101, s[0:1], s33, 1
	v_lshlrev_b32_e32 v102, 5, v101
	s_lshl_b32 s3, s46, 5
	v_add_u32_e32 v36, v0, v53
	v_lshlrev_b32_e32 v91, 1, v30
	v_mov_b32_e32 v97, s39
	v_add_u32_e32 v103, s39, v102
	s_add_i32 s39, s39, s3
	v_lshl_add_u32 v42, v36, 4, v37
	v_add_u32_e32 v36, v55, v0
	v_mov_b32_e32 v37, 0x4000
	v_lshl_add_u32 v44, v36, 4, v37
	v_lshlrev_b32_e32 v86, 3, v30
	v_add_u32_e32 v37, s39, v91
	v_cmp_eq_u32_e64 s[38:39], 0, v45
	v_lshlrev_b32_e32 v150, 7, v32
	v_lshlrev_b32_e32 v152, 7, v68
	v_lshlrev_b32_e32 v153, 7, v69
	v_lshl_or_b32 v174, v45, 10, v86
	v_cndmask_b32_e64 v45, 0, v89, s[38:39]
	v_lshl_add_u32 v147, v30, 2, s42
	v_add_u32_e32 v68, s44, v150
	v_add_u32_e32 v69, s44, v151
	v_add_u32_e32 v93, s44, v152
	v_add_u32_e32 v94, s44, v153
	v_mad_u32_u24 v156, v30, 48, s45
	v_lshlrev_b32_e32 v159, 2, v38
	s_add_i32 s3, 0, 0x1b200
	v_lshl_or_b32 v38, v101, 4, v30
	v_lshl_add_u32 v45, v30, 4, v45
	v_mul_u32_u24_e32 v48, 0x110, v30
	v_mul_u32_u24_e32 v50, 0x90, v30
	v_lshlrev_b32_e32 v30, 1, v35
	v_add_u32_e32 v96, s41, v1
	v_lshlrev_b32_e32 v160, 2, v39
	v_mov_b32_e32 v39, s3
	s_movk_i32 s3, 0x90
	v_add_u32_e32 v186, v68, v30
	v_add_u32_e32 v187, v69, v30
	v_add_u32_e32 v188, v93, v30
	v_add_u32_e32 v189, v94, v30
	v_lshlrev_b32_e32 v30, 1, v34
	v_lshlrev_b32_e32 v168, 2, v47
	v_mad_u32_u24 v47, v96, s3, v97
	v_mad_u32_u24 v175, v92, s3, v97
	v_mad_i32_i24 v176, v38, s3, v97
	v_add_u32_e32 v190, v68, v30
	v_add_u32_e32 v191, v69, v30
	v_add_u32_e32 v192, v93, v30
	v_add_u32_e32 v193, v94, v30
	v_lshlrev_b32_e32 v30, 1, v33
	v_lshlrev_b32_e32 v161, 2, v40
	v_mad_u32_u24 v40, v100, s3, v97
	v_mad_u32_u24 v177, v98, s3, v97
	v_mad_u32_u24 v38, v31, s3, 0
	v_mad_u32_u24 v39, v31, s3, v39
	v_add_u32_e32 v194, v68, v30
	v_add_u32_e32 v195, v69, v30
	v_add_u32_e32 v196, v93, v30
	v_add_u32_e32 v197, v94, v30
	v_add_u32_e32 v30, s2, v175
	v_add_u32_e32 v33, s2, v176
	v_add_u32_e32 v198, s2, v47
	v_cmp_eq_u32_e64 s[2:3], 0, v1
	v_lshl_add_u32 v95, v1, 1, s43
	s_mulk_i32 s33, 0x900
	v_writelane_b32 v250, s2, 39
	v_add_u32_e32 v184, 0, v90
	v_lshlrev_b32_e32 v155, 3, v56
	v_writelane_b32 v250, s3, 40
	v_cndmask_b32_e64 v90, 0, 1.0, s[2:3]
	s_add_i32 s2, s54, s70
	v_add_u32_e32 v178, s33, v95
	s_lshl_b32 s33, s2, 7
	s_movk_i32 s2, 0x300
	v_lshl_add_u32 v148, v32, 2, s42
	v_add_u32_e32 v56, s43, v155
	v_cmp_gt_u32_e64 s[42:43], s2, v0
	s_movk_i32 s2, 0x100
	v_add_u32_e32 v149, s44, v91
	v_cmp_gt_u32_e64 s[44:45], s2, v0
	s_mov_b32 s2, s54
	v_writelane_b32 v250, s2, 6
	v_or_b32_e32 v183, 3, v31
	s_mov_b32 s81, 0
	v_writelane_b32 v250, s3, 7
	v_cmp_gt_u32_e64 s[2:3], 2, v1
	v_lshlrev_b32_e32 v167, 2, v46
	v_mov_b32_e32 v46, 0x3db504f3
	v_writelane_b32 v250, s2, 41
	v_and_b32_e32 v180, 60, v31
	v_mul_u32_u24_e32 v31, 0x110, v183
	v_writelane_b32 v250, s3, 42
	v_cmp_gt_u32_e64 s[2:3], 4, v1
	v_and_b32_e32 v185, 48, v0
	s_mov_b32 s82, s81
	v_writelane_b32 v250, s2, 43
	s_mov_b32 s83, s81
	v_cndmask_b32_e32 v67, 0, v67, vcc
	v_writelane_b32 v250, s3, 44
	v_cmp_gt_u32_e64 s[2:3], 8, v1
	v_lshlrev_b32_e32 v162, 2, v41
	v_lshlrev_b32_e32 v164, 2, v43
	v_writelane_b32 v250, s2, 45
	v_add_u32_e32 v41, 0, v52
	v_add_u32_e32 v43, 0, v54
	v_writelane_b32 v250, s3, 46
	v_cmp_eq_u32_e64 s[2:3], 63, v1
	v_and_b32_e32 v36, 16, v0
	v_cndmask_b32_e64 v179, 1.0, v46, s[38:39]
	v_writelane_b32 v250, s2, 47
	v_mov_b32_e32 v89, 0
	v_mul_u32_u24_e32 v46, 0x110, v180
	v_writelane_b32 v250, s3, 48
	v_cmp_gt_u32_e64 s[2:3], 62, v1
	v_add_u32_e32 v49, 0, v185
	v_add_u32_e32 v34, v103, v91
	v_writelane_b32 v250, s2, 49
	v_mul_u32_u24_e32 v32, 0x90, v32
	v_lshlrev_b32_e32 v35, 1, v99
	v_writelane_b32 v250, s3, 50
	v_cmp_gt_u32_e64 s[2:3], 60, v1
	v_mul_u32_u24_e32 v47, 0x90, v58
	v_lshlrev_b32_e32 v51, 1, v58
	v_writelane_b32 v250, s2, 51
	v_lshlrev_b32_e32 v52, 1, v57
	s_ashr_i32 s71, s70, 31
	v_writelane_b32 v250, s3, 52
	v_cmp_gt_u32_e64 s[2:3], 56, v1
	s_mov_b32 s80, s81
	v_mov_b64_e32 v[236:237], s[82:83]
	v_writelane_b32 v250, s2, 53
	v_add_u32_e32 v211, v45, v31
	v_or_b32_e32 v181, 1, v180
	v_writelane_b32 v250, s3, 54
	v_cmp_gt_u32_e64 s[2:3], 48, v1
	v_or_b32_e32 v182, 2, v180
	v_cvt_pk_bf16_f32 v199, v90, s0
	v_add_u32_e32 v200, v102, v185
	v_or_b32_e32 v201, v60, v61
	v_bitop3_b32 v202, v60, v61, v60 bitop3:3
	v_or_b32_e32 v203, v62, v63
	v_bitop3_b32 v204, v62, v63, v62 bitop3:3
	v_or_b32_e32 v205, v64, v65
	v_bitop3_b32 v206, v64, v65, v64 bitop3:3
	v_or_b32_e32 v207, v66, v67
	v_bitop3_b32 v208, v66, v67, v66 bitop3:3
	v_mov_b32_e32 v92, v90
	v_mov_b32_e32 v93, v90
	v_mov_b64_e32 v[234:235], s[80:81]
	v_add_u32_e32 v209, v41, v42
	v_add_u32_e32 v210, v43, v44
	v_mov_b32_e32 v212, 0x3ecc95a3
	v_add_u32_e32 v213, v88, v185
	v_add_u32_e32 v214, v49, v48
	v_add_u32_e32 v215, v30, v185
	v_add_u32_e32 v216, v34, v32
	v_add_u32_e32 v217, v33, v155
	v_add_u32_e32 v218, v40, v185
	v_add_u32_e32 v219, v157, v35
	v_add_u32_e32 v220, v37, v47
	v_add_u32_e32 v221, v177, v51
	v_add_u32_e32 v222, v38, v52
	v_add_u32_e32 v223, v39, v52
	v_mov_b32_e32 v30, v89
	v_mov_b32_e32 v31, v89
	v_mov_b32_e32 v32, v89
	v_mov_b32_e32 v33, v89
	v_add_u32_e32 v224, v45, v46
	v_mov_b32_e32 v94, 0x3f317218
	v_mov_b32_e32 v225, 0x7f800000
	v_mov_b32_e32 v226, 0x7fc00000
	v_mov_b32_e32 v227, 0xff800000
	v_add_u32_e32 v228, v56, v50
	v_add_u32_e32 v229, v59, v185
	s_lshl_b32 s40, s70, 7
	s_lshl_b32 s41, s54, 3
	s_lshl_b32 s48, s70, 3
	s_add_i32 s49, 0, 0x18e00
	s_movk_i32 s50, 0x3000
	s_mov_b32 s51, 0xbfb8aa3b
	s_mov_b32 s52, 0x800000
	s_mov_b32 s53, s54
	v_cmp_ne_u32_e64 s[46:47], 0, v36
	v_cmp_gt_u32_e64 s[54:55], 16, v1
	v_writelane_b32 v250, s2, 55
	v_cmp_gt_u32_e64 s[66:67], 32, v1
	s_lshl_b64 s[82:83], s[70:71], 10
	s_lshl_b64 s[92:93], s[70:71], 14
	v_writelane_b32 v250, s3, 56
	v_readfirstlane_b32 s2, v0
	s_lshr_b32 s2, s2, 6
	s_mul_i32 s3, s2, s48
	s_add_i32 s3, s3, s41
	s_and_b32 s71, s3, 0xffffffc0
	s_and_b32 s68, s53, 7
	s_mul_i32 s88, s2, s82
	s_mov_b32 s89, 0
	s_lshl_b32 s3, s2, 10
	s_add_i32 s3, s3, 0x1c200
	v_lshl_add_u64 v[56:57], v[80:81], 0, s[88:89]
	v_add_u32_e32 v58, s3, v184
	v_or_b32_e32 v34, s71, v1
	v_ashrrev_i32_e32 v35, 31, v34
	v_readlane_b32 s2, v250, 12
	v_lshlrev_b64 v[34:35], 7, v[34:35]
	v_readlane_b32 s3, v250, 13
	s_lshl_b32 s80, s68, 2
	v_mov_b32_e32 v38, s80
	v_lshl_add_u64 v[34:35], s[2:3], 0, v[34:35]
	v_readlane_b32 s2, v250, 4
	v_readlane_b32 s3, v250, 5
	v_lshl_add_u64 v[34:35], v[34:35], 0, s[80:81]
	s_nop 3
	global_load_dword v39, v38, s[2:3]
	global_load_dword v37, v[34:35], off
	global_load_dword v40, v[34:35], off offset:64
	global_load_dword v36, v[34:35], off offset:32
	s_nop 0
	global_load_dword v38, v38, s[78:79]
	s_add_u32 s68, s78, s80
	s_addc_u32 s69, s79, 0
	s_add_u32 s88, s2, s80
	s_mov_b32 s2, 0x41a00000
	s_addc_u32 s89, s3, 0
	global_load_dword v59, v[34:35], off offset:96
	global_load_dword v60, v89, s[88:89] offset:32
	global_load_dword v61, v89, s[68:69] offset:32
	s_waitcnt vmcnt(5)
	v_add_f32_e32 v39, v40, v39
	v_cmp_nlt_f32_e32 vcc, s2, v39
	s_and_saveexec_b64 s[2:3], vcc
	s_cbranch_execz .Lp3pre_330
	v_mul_f32_e32 v39, 0x3fb8aa3b, v39
	v_exp_f32_e32 v39, v39
	s_mov_b32 s71, 0x3f2aaaab
	v_add_f32_e32 v42, 1.0, v39
	v_frexp_mant_f32_e32 v44, v42
	v_cvt_f64_f32_e32 v[40:41], v42
	v_frexp_exp_i32_f64_e32 v40, v[40:41]
	v_cmp_gt_f32_e32 vcc, s71, v44
	v_add_f32_e32 v43, -1.0, v42
	v_sub_f32_e32 v45, v43, v42
	v_subbrev_co_u32_e32 v48, vcc, 0, v40, vcc
	v_sub_u32_e32 v40, 0, v48
	v_sub_f32_e32 v43, v39, v43
	v_add_f32_e32 v45, 1.0, v45
	v_ldexp_f32 v41, v42, v40
	v_add_f32_e32 v43, v43, v45
	v_add_f32_e32 v42, -1.0, v41
	v_add_f32_e32 v44, 1.0, v41
	v_ldexp_f32 v40, v43, v40
	v_add_f32_e32 v43, 1.0, v42
	v_add_f32_e32 v45, -1.0, v44
	v_sub_f32_e32 v43, v41, v43
	v_sub_f32_e32 v41, v41, v45
	v_add_f32_e32 v43, v40, v43
	v_add_f32_e32 v40, v40, v41
	v_add_f32_e32 v49, v44, v40
	v_rcp_f32_e32 v51, v49
	v_sub_f32_e32 v41, v49, v44
	v_sub_f32_e32 v50, v40, v41
	v_add_f32_e32 v41, v42, v43
	v_mul_f32_e32 v53, v41, v51
	v_sub_f32_e32 v40, v41, v42
	v_mul_f32_e32 v42, v49, v53
	v_fma_f32 v44, v53, v49, -v42
	v_fmac_f32_e32 v44, v53, v50
	v_sub_f32_e32 v52, v43, v40
	v_add_f32_e32 v40, v42, v44
	v_sub_f32_e32 v43, v41, v40
	v_pk_add_f32 v[46:47], v[40:41], v[42:43] neg_lo:[0,1] neg_hi:[0,1]
	v_mov_b32_e32 v45, v40
	v_pk_add_f32 v[40:41], v[46:47], v[44:45] neg_lo:[0,1] neg_hi:[0,1]
	s_mov_b32 s71, 0x3f317218
	v_add_f32_e32 v41, v52, v41
	v_add_f32_e32 v40, v40, v41
	v_add_f32_e32 v41, v43, v40
	v_mul_f32_e32 v52, v51, v41
	v_mul_f32_e32 v42, v49, v52
	v_fma_f32 v44, v52, v49, -v42
	v_fmac_f32_e32 v44, v52, v50
	v_sub_f32_e32 v43, v43, v41
	v_add_f32_e32 v49, v40, v43
	v_add_f32_e32 v40, v42, v44
	v_sub_f32_e32 v43, v41, v40
	v_pk_add_f32 v[46:47], v[40:41], v[42:43] neg_lo:[0,1] neg_hi:[0,1]
	v_mov_b32_e32 v45, v40
	v_pk_add_f32 v[40:41], v[46:47], v[44:45] neg_lo:[0,1] neg_hi:[0,1]
	s_nop 0
	v_add_f32_e32 v41, v49, v41
	v_add_f32_e32 v40, v40, v41
	v_add_f32_e32 v41, v53, v52
	v_add_f32_e32 v40, v43, v40
	v_sub_f32_e32 v42, v41, v53
	v_mul_f32_e32 v40, v51, v40
	v_sub_f32_e32 v42, v52, v42
	v_add_f32_e32 v42, v42, v40
	v_add_f32_e32 v44, v41, v42
	v_mul_f32_e32 v45, v44, v44
	v_fmamk_f32 v40, v45, 0x3e9b6dac, v212
	v_fmaak_f32 v95, v45, v40, 0x3f2aaada
	v_cvt_f32_i32_e32 v40, v48
	v_sub_f32_e32 v41, v44, v41
	v_sub_f32_e32 v41, v42, v41
	v_ldexp_f32 v46, v41, 1
	v_mul_f32_e32 v41, v44, v45
	v_ldexp_f32 v43, v44, 1
	v_pk_mul_f32 v[44:45], v[40:41], v[94:95]
	s_nop 0
	v_fma_f32 v42, v40, s71, -v44
	v_fmac_f32_e32 v42, 0xb102e308, v40
	v_pk_add_f32 v[40:41], v[44:45], v[42:43]
	s_mov_b32 s71, 0x7f800000
	v_sub_f32_e32 v43, v41, v43
	v_sub_f32_e32 v43, v45, v43
	v_add_f32_e32 v47, v46, v43
	v_mov_b32_e32 v46, v44
	v_pk_add_f32 v[44:45], v[40:41], v[44:45] neg_lo:[0,1] neg_hi:[0,1]
	v_pk_add_f32 v[48:49], v[40:41], v[46:47]
	v_mov_b32_e32 v43, v40
	v_mov_b32_e32 v45, v49
	v_pk_add_f32 v[50:51], v[42:43], v[44:45] neg_lo:[0,1] neg_hi:[0,1]
	v_pk_add_f32 v[42:43], v[42:43], v[44:45]
	v_mov_b32_e32 v46, v47
	v_pk_add_f32 v[44:45], v[42:43], v[40:41] op_sel:[1,0] op_sel_hi:[0,1] neg_lo:[0,1] neg_hi:[0,1]
	v_pk_add_f32 v[52:53], v[48:49], v[44:45] op_sel_hi:[1,0] neg_lo:[0,1] neg_hi:[0,1]
	v_mov_b32_e32 v48, v49
	v_mov_b32_e32 v49, v43
	v_pk_mov_b32 v[44:45], v[40:41], v[44:45] op_sel:[1,0]
	v_mov_b32_e32 v47, v40
	v_pk_add_f32 v[44:45], v[48:49], v[44:45] neg_lo:[0,1] neg_hi:[0,1]
	v_mov_b32_e32 v52, v50
	v_pk_add_f32 v[40:41], v[46:47], v[44:45] neg_lo:[0,1] neg_hi:[0,1]
	v_mov_b32_e32 v51, v43
	v_pk_add_f32 v[44:45], v[52:53], v[40:41]
	v_cmp_neq_f32_e32 vcc, s71, v39
	v_pk_add_f32 v[46:47], v[44:45], v[44:45] op_sel:[0,1] op_sel_hi:[1,0]
	s_mov_b32 s71, 0x33800000
	v_pk_add_f32 v[42:43], v[42:43], v[46:47] op_sel:[1,0] op_sel_hi:[0,1]
	v_mov_b32_e32 v45, v42
	v_pk_add_f32 v[48:49], v[44:45], v[50:51] neg_lo:[0,1] neg_hi:[0,1]
	v_mov_b32_e32 v41, v46
	v_sub_f32_e32 v43, v44, v48
	v_pk_add_f32 v[40:41], v[40:41], v[48:49] neg_lo:[0,1] neg_hi:[0,1]
	v_sub_f32_e32 v43, v50, v43
	v_add_f32_e32 v40, v40, v43
	v_add_f32_e32 v40, v40, v41
	v_add_f32_e32 v40, v42, v40
	v_cndmask_b32_e32 v40, v225, v40, vcc
	v_cmp_ngt_f32_e32 vcc, -1.0, v39
	s_nop 1
	v_cndmask_b32_e32 v40, v226, v40, vcc
	v_cmp_neq_f32_e32 vcc, -1.0, v39
	s_nop 1
	v_cndmask_b32_e32 v40, v227, v40, vcc
	v_cmp_lt_f32_e64 vcc, |v39|, s71
	s_nop 1
	v_cndmask_b32_e32 v39, v40, v39, vcc
.Lp3pre_330:
	s_or_b64 exec, exec, s[2:3]
	s_mov_b32 s2, 0x41a00000
	s_waitcnt vmcnt(1)
	v_mov_b32_e32 v35, v59
	v_mov_b32_e32 v40, v60
	v_add_f32_e32 v35, v35, v40
	v_cmp_nlt_f32_e32 vcc, s2, v35
	s_and_saveexec_b64 s[2:3], vcc
	s_cbranch_execz .Lp3pre_332
	v_mul_f32_e32 v35, 0x3fb8aa3b, v35
	v_exp_f32_e32 v35, v35
	s_mov_b32 s68, 0x3f2aaaab
	v_add_f32_e32 v42, 1.0, v35
	v_frexp_mant_f32_e32 v44, v42
	v_cvt_f64_f32_e32 v[40:41], v42
	v_frexp_exp_i32_f64_e32 v40, v[40:41]
	v_cmp_gt_f32_e32 vcc, s68, v44
	v_add_f32_e32 v43, -1.0, v42
	v_sub_f32_e32 v45, v43, v42
	v_subbrev_co_u32_e32 v48, vcc, 0, v40, vcc
	v_sub_u32_e32 v40, 0, v48
	v_sub_f32_e32 v43, v35, v43
	v_add_f32_e32 v45, 1.0, v45
	v_ldexp_f32 v41, v42, v40
	v_add_f32_e32 v43, v43, v45
	v_add_f32_e32 v42, -1.0, v41
	v_add_f32_e32 v44, 1.0, v41
	v_ldexp_f32 v40, v43, v40
	v_add_f32_e32 v43, 1.0, v42
	v_add_f32_e32 v45, -1.0, v44
	v_sub_f32_e32 v43, v41, v43
	v_sub_f32_e32 v41, v41, v45
	v_add_f32_e32 v43, v40, v43
	v_add_f32_e32 v40, v40, v41
	v_add_f32_e32 v49, v44, v40
	v_rcp_f32_e32 v51, v49
	v_sub_f32_e32 v41, v49, v44
	v_sub_f32_e32 v50, v40, v41
	v_add_f32_e32 v41, v42, v43
	v_mul_f32_e32 v53, v41, v51
	v_sub_f32_e32 v40, v41, v42
	v_mul_f32_e32 v42, v49, v53
	v_fma_f32 v44, v53, v49, -v42
	v_fmac_f32_e32 v44, v53, v50
	v_sub_f32_e32 v52, v43, v40
	v_add_f32_e32 v40, v42, v44
	v_sub_f32_e32 v43, v41, v40
	v_pk_add_f32 v[46:47], v[40:41], v[42:43] neg_lo:[0,1] neg_hi:[0,1]
	v_mov_b32_e32 v45, v40
	v_pk_add_f32 v[40:41], v[46:47], v[44:45] neg_lo:[0,1] neg_hi:[0,1]
	s_mov_b32 s68, 0x3f317218
	v_add_f32_e32 v41, v52, v41
	v_add_f32_e32 v40, v40, v41
	v_add_f32_e32 v41, v43, v40
	v_mul_f32_e32 v52, v51, v41
	v_mul_f32_e32 v42, v49, v52
	v_fma_f32 v44, v52, v49, -v42
	v_fmac_f32_e32 v44, v52, v50
	v_sub_f32_e32 v43, v43, v41
	v_add_f32_e32 v49, v40, v43
	v_add_f32_e32 v40, v42, v44
	v_sub_f32_e32 v43, v41, v40
	v_pk_add_f32 v[46:47], v[40:41], v[42:43] neg_lo:[0,1] neg_hi:[0,1]
	v_mov_b32_e32 v45, v40
	v_pk_add_f32 v[40:41], v[46:47], v[44:45] neg_lo:[0,1] neg_hi:[0,1]
	s_nop 0
	v_add_f32_e32 v41, v49, v41
	v_add_f32_e32 v40, v40, v41
	v_add_f32_e32 v41, v53, v52
	v_add_f32_e32 v40, v43, v40
	v_sub_f32_e32 v42, v41, v53
	v_mul_f32_e32 v40, v51, v40
	v_sub_f32_e32 v42, v52, v42
	v_add_f32_e32 v42, v42, v40
	v_add_f32_e32 v44, v41, v42
	v_mul_f32_e32 v45, v44, v44
	v_fmamk_f32 v40, v45, 0x3e9b6dac, v212
	v_fmaak_f32 v95, v45, v40, 0x3f2aaada
	v_cvt_f32_i32_e32 v40, v48
	v_sub_f32_e32 v41, v44, v41
	v_sub_f32_e32 v41, v42, v41
	v_ldexp_f32 v46, v41, 1
	v_mul_f32_e32 v41, v44, v45
	v_ldexp_f32 v43, v44, 1
	v_pk_mul_f32 v[44:45], v[40:41], v[94:95]
	s_nop 0
	v_fma_f32 v42, v40, s68, -v44
	v_fmac_f32_e32 v42, 0xb102e308, v40
	v_pk_add_f32 v[40:41], v[44:45], v[42:43]
	s_mov_b32 s68, 0x7f800000
	v_sub_f32_e32 v43, v41, v43
	v_sub_f32_e32 v43, v45, v43
	v_add_f32_e32 v47, v46, v43
	v_mov_b32_e32 v46, v44
	v_pk_add_f32 v[44:45], v[40:41], v[44:45] neg_lo:[0,1] neg_hi:[0,1]
	v_pk_add_f32 v[48:49], v[40:41], v[46:47]
	v_mov_b32_e32 v43, v40
	v_mov_b32_e32 v45, v49
	v_pk_add_f32 v[50:51], v[42:43], v[44:45] neg_lo:[0,1] neg_hi:[0,1]
	v_pk_add_f32 v[42:43], v[42:43], v[44:45]
	v_mov_b32_e32 v46, v47
	v_pk_add_f32 v[44:45], v[42:43], v[40:41] op_sel:[1,0] op_sel_hi:[0,1] neg_lo:[0,1] neg_hi:[0,1]
	v_pk_add_f32 v[52:53], v[48:49], v[44:45] op_sel_hi:[1,0] neg_lo:[0,1] neg_hi:[0,1]
	v_mov_b32_e32 v48, v49
	v_mov_b32_e32 v49, v43
	v_pk_mov_b32 v[44:45], v[40:41], v[44:45] op_sel:[1,0]
	v_mov_b32_e32 v47, v40
	v_pk_add_f32 v[44:45], v[48:49], v[44:45] neg_lo:[0,1] neg_hi:[0,1]
	v_mov_b32_e32 v52, v50
	v_pk_add_f32 v[40:41], v[46:47], v[44:45] neg_lo:[0,1] neg_hi:[0,1]
	v_mov_b32_e32 v51, v43
	v_pk_add_f32 v[44:45], v[52:53], v[40:41]
	v_cmp_neq_f32_e32 vcc, s68, v35
	v_pk_add_f32 v[46:47], v[44:45], v[44:45] op_sel:[0,1] op_sel_hi:[1,0]
	s_mov_b32 s68, 0x33800000
	v_pk_add_f32 v[42:43], v[42:43], v[46:47] op_sel:[1,0] op_sel_hi:[0,1]
	v_mov_b32_e32 v45, v42
	v_pk_add_f32 v[48:49], v[44:45], v[50:51] neg_lo:[0,1] neg_hi:[0,1]
	v_mov_b32_e32 v41, v46
	v_sub_f32_e32 v43, v44, v48
	v_pk_add_f32 v[40:41], v[40:41], v[48:49] neg_lo:[0,1] neg_hi:[0,1]
	v_sub_f32_e32 v43, v50, v43
	v_add_f32_e32 v40, v40, v43
	v_add_f32_e32 v40, v40, v41
	v_add_f32_e32 v40, v42, v40
	v_cndmask_b32_e32 v40, v225, v40, vcc
	v_cmp_ngt_f32_e32 vcc, -1.0, v35
	s_nop 1
	v_cndmask_b32_e32 v40, v226, v40, vcc
	v_cmp_neq_f32_e32 vcc, -1.0, v35
	s_nop 1
	v_cndmask_b32_e32 v40, v227, v40, vcc
	v_cmp_lt_f32_e64 vcc, |v35|, s68
	s_nop 1
	v_cndmask_b32_e32 v35, v40, v35, vcc
.Lp3pre_332:
	s_or_b64 exec, exec, s[2:3]
	v_mul_f32_e32 v40, 0x3fb8aa3b, v38
	v_rndne_f32_e32 v41, v40
	s_mov_b32 s2, 0x3fb8aa3b
	v_sub_f32_e32 v42, v40, v41
	v_fma_f32 v40, v38, s2, -v40
	v_fmac_f32_e32 v40, 0x32a5705f, v38
	v_add_f32_e32 v40, v42, v40
	v_cvt_i32_f32_e32 v41, v41
	v_exp_f32_e32 v40, v40
	s_mov_b32 s3, 0xc2ce8ed0
	v_cmp_ngt_f32_e32 vcc, s3, v38
	v_mul_f32_e32 v37, 0xbfb8aa3b, v37
	v_ldexp_f32 v40, v40, v41
	s_waitcnt vmcnt(0)
	v_mov_b32_e32 v34, v61
	v_mul_f32_e32 v41, 0x3fb8aa3b, v34
	v_rndne_f32_e32 v42, v41
	v_sub_f32_e32 v43, v41, v42
	v_fma_f32 v41, v34, s2, -v41
	v_fmac_f32_e32 v41, 0x32a5705f, v34
	v_add_f32_e32 v41, v43, v41
	v_exp_f32_e32 v41, v41
	v_cvt_i32_f32_e32 v42, v42
	s_mov_b32 s2, 0x42b17218
	v_cndmask_b32_e32 v40, 0, v40, vcc
	v_cmp_nlt_f32_e32 vcc, s2, v38
	v_ldexp_f32 v41, v41, v42
	v_mul_f32_e32 v36, 0xbfb8aa3b, v36
	v_cndmask_b32_e32 v38, v225, v40, vcc
	v_cmp_ngt_f32_e32 vcc, s3, v34
	v_mul_f32_e64 v40, v39, -v38
	ds_bpermute_b32 v42, v162, v40
	v_cndmask_b32_e32 v41, 0, v41, vcc
	v_cmp_nlt_f32_e32 vcc, s2, v34
	v_readlane_b32 s2, v250, 39
	v_readlane_b32 s3, v250, 40
	v_cndmask_b32_e32 v34, v225, v41, vcc
	v_mul_f32_e64 v41, v35, -v34
	ds_bpermute_b32 v43, v168, v41
	s_waitcnt lgkmcnt(1)
	v_fma_f32 v38, v39, -v38, v42
	v_cndmask_b32_e64 v38, v38, v40, s[2:3]
	v_readlane_b32 s2, v250, 47
	ds_bpermute_b32 v39, v163, v38
	s_waitcnt lgkmcnt(1)
	v_fma_f32 v34, v35, -v34, v43
	v_readlane_b32 s3, v250, 48
	v_exp_f32_e32 v37, v37
	v_exp_f32_e32 v36, v36
	v_cndmask_b32_e64 v34, v34, v41, s[2:3]
	ds_bpermute_b32 v35, v169, v34
	v_readlane_b32 s2, v250, 41
	s_waitcnt lgkmcnt(1)
	v_add_f32_e32 v39, v38, v39
	v_readlane_b32 s3, v250, 42
	v_add_f32_e32 v37, 1.0, v37
	s_waitcnt lgkmcnt(0)
	v_add_f32_e32 v35, v34, v35
	v_cndmask_b32_e64 v38, v39, v38, s[2:3]
	v_readlane_b32 s2, v250, 49
	ds_bpermute_b32 v39, v164, v38
	v_readlane_b32 s3, v250, 50
	v_add_f32_e32 v36, 1.0, v36
	v_rcp_f32_e32 v37, v37
	v_cndmask_b32_e64 v34, v34, v35, s[2:3]
	ds_bpermute_b32 v35, v170, v34
	v_readlane_b32 s2, v250, 43
	s_waitcnt lgkmcnt(1)
	v_add_f32_e32 v39, v38, v39
	v_readlane_b32 s3, v250, 44
	v_rcp_f32_e32 v36, v36
	s_waitcnt lgkmcnt(0)
	v_add_f32_e32 v35, v34, v35
	v_cndmask_b32_e64 v38, v39, v38, s[2:3]
	v_readlane_b32 s2, v250, 51
	ds_bpermute_b32 v39, v165, v38
	v_readlane_b32 s3, v250, 52
	s_waitcnt lgkmcnt(0)
	v_add_f32_e32 v39, v38, v39
	v_cndmask_b32_e64 v34, v34, v35, s[2:3]
	ds_bpermute_b32 v35, v171, v34
	v_readlane_b32 s2, v250, 45
	v_readlane_b32 s3, v250, 46
	s_waitcnt lgkmcnt(0)
	v_add_f32_e32 v35, v34, v35
	v_cndmask_b32_e64 v38, v39, v38, s[2:3]
	v_readlane_b32 s2, v250, 53
	v_readlane_b32 s3, v250, 54
	ds_bpermute_b32 v39, v166, v38
	s_waitcnt lgkmcnt(0)
	v_add_f32_e32 v39, v38, v39
	v_cndmask_b32_e64 v34, v34, v35, s[2:3]
	ds_bpermute_b32 v35, v172, v34
	v_readlane_b32 s2, v250, 55
	v_readlane_b32 s3, v250, 56
	v_cndmask_b32_e64 v38, v39, v38, s[54:55]
	ds_bpermute_b32 v39, v167, v38
	s_waitcnt lgkmcnt(1)
	v_add_f32_e32 v35, v34, v35
	v_cndmask_b32_e64 v34, v34, v35, s[2:3]
	ds_bpermute_b32 v35, v173, v34
	s_waitcnt lgkmcnt(1)
	v_add_f32_e32 v39, v38, v39
	v_cndmask_b32_e64 v38, v39, v38, s[66:67]
	s_waitcnt lgkmcnt(0)
	v_add_f32_e32 v35, v34, v35
	v_cndmask_b32_e64 v40, v34, v35, s[66:67]
	v_lshl_add_u64 v[34:35], s[74:75], 0, v[56:57]
	v_add_co_u32_e32 v34, vcc, 0x2b4000, v34
	ds_write2st64_b32 v58, v38, v40 offset0:136 offset1:137
	ds_write2st64_b32 v58, v37, v36 offset0:138 offset1:139
	v_addc_co_u32_e32 v35, vcc, 0, v35, vcc
	global_store_dword v[34:35], v38, off
	global_store_dword v[34:35], v40, off offset:256
	global_store_dword v[34:35], v37, off offset:512
	global_store_dword v[34:35], v36, off offset:768
	s_waitcnt lgkmcnt(0)
	s_barrier
	s_branch .LBB0_313

.Lp4n_tab:
	v_mbcnt_lo_u32_b32 v229, -1, 0
	v_mbcnt_hi_u32_b32 v229, -1, v229
	v_and_b32_e32 v230, s61, v229
	v_lshrrev_b32_e32 v231, s62, v229
	v_lshrrev_b32_e32 v232, 1, v231
	v_add_u32_e32 v232, s59, v232
	v_and_b32_e32 v232, 7, v232
	v_add_u32_e32 v233, s60, v231
	v_and_b32_e32 v233, 1, v233
	v_sub_u32_e32 v234, s61, v230
	v_cmp_eq_u32_e32 vcc, 1, v233
	s_nop 1
	v_cndmask_b32_e32 v235, v230, v234, vcc
	v_add_u32_e32 v235, s64, v235
	v_cmp_eq_u32_e32 vcc, s61, v230
	s_nop 1
	v_cndmask_b32_e64 v236, 0, 1, vcc
	v_lshlrev_b32_e32 v237, 9, v232
	v_or_b32_e32 v220, v235, v237
	v_lshlrev_b32_e32 v237, 12, v233
	v_or_b32_e32 v220, v220, v237
	s_lshl_b32 s45, s57, 13
	s_lshl_b32 s46, s58, 15
	s_or_b32 s45, s45, s46
	s_lshl_b32 s46, s63, 20
	s_or_b32 s45, s45, s46
	v_or_b32_e32 v220, s45, v220
	v_lshlrev_b32_e32 v237, 21, v236
	v_or_b32_e32 v220, v220, v237
	v_lshlrev_b32_e32 v237, 22, v230
	v_or_b32_e32 v220, v220, v237
	v_lshl_add_u32 v237, v235, 3, v232
	v_lshlrev_b32_e32 v221, 14, v237
	v_lshlrev_b32_e32 v238, 8, v233
	v_lshl_add_u32 v224, v237, 10, v238
	v_lshlrev_b32_e32 v238, 8, v232
	v_lshl_add_u32 v222, v235, 17, v238
	s_mov_b32 s45, 0xc0000
	v_mul_lo_u32 v237, v235, s45
	s_lshl_b32 s46, s57, 6
	s_sub_u32 s46, s46, 0x5000
	v_add_u32_e32 v238, s46, v238
	v_add_u32_e32 v223, v237, v238
	s_mov_b32 s45, 0x60000
	v_mul_lo_u32 v237, v235, s45
	v_lshlrev_b32_e32 v238, 10, v233
	v_lshl_add_u32 v238, v232, 7, v238
	s_lshl_b32 s46, s57, 5
	v_add_u32_e32 v238, s46, v238
	v_add_u32_e32 v227, v237, v238
	v_lshlrev_b32_e32 v228, 6, v235
	v_mov_b32_e32 v225, s65
	v_mov_b32_e32 v226, s66
	s_mov_b32 s99, 0
	v_lshlrev_b32_e32 v253, 2, v189
	v_add_u32_e32 v254, 0x1d900, v253
	v_add_u32_e32 v253, 0x1d400, v253
	v_add_u32_e32 v197, v173, v182
	v_mov_b32_e32 v251, 0x1d400
	v_mov_b32_e32 v252, 0x1d900
	v_add_u32_e32 v255, 0x1da00, v180
	v_add_u32_e32 v247, 0x3000, v120
	v_add_u32_e32 v248, 0x6000, v120
	v_add_u32_e32 v249, 0x9000, v120
	v_lshlrev_b32_e32 v239, 4, v0
	v_add_u32_e32 v240, 0x2000, v239
	v_mov_b32_e32 v241, v118
	v_add_u32_e32 v242, 0x10000, v118
	s_mov_b32 s100, 0xbfb8aa3b
	s_mov_b32 s101, 0xbfb8aa3b
	s_nop 1
	v_readlane_b32 s41, v220, 0
	v_readlane_b32 s42, v220, 1
	v_readlane_b32 s43, v220, 2
.Lp4n_top_A:
	s_cmp_lt_u32 s99, 63
	s_cselect_b64 s[10:11], -1, 0
	ds_read_b128 v[102:105], v193 offset:31232
	ds_read_b128 v[106:109], v192 offset:48640
	ds_read_b128 v[110:113], v192 offset:48704
	ds_read_b128 v[114:117], v193 offset:31296
	ds_read_b128 v[198:201], v190
	ds_read_b128 v[202:205], v190 offset:64
	s_waitcnt lgkmcnt(0)
	v_mfma_f32_16x16x32_bf16 v[102:105], v[102:105], v[106:109], 0
	s_waitcnt lgkmcnt(1)
	v_mfma_f32_16x16x32_bf16 v[106:109], v[198:201], v[106:109], 0
	v_mfma_f32_16x16x32_bf16 v[102:105], v[114:117], v[110:113], v[102:105]
	ds_read_b128 v[114:117], v193 offset:31360
	ds_read_b128 v[198:201], v192 offset:48768
	s_waitcnt lgkmcnt(2)
	v_mfma_f32_16x16x32_bf16 v[106:109], v[202:205], v[110:113], v[106:109]
	ds_read_b128 v[110:113], v193 offset:31424
	ds_read_b128 v[202:205], v192 offset:48832
	s_waitcnt lgkmcnt(2)
	v_mfma_f32_16x16x32_bf16 v[102:105], v[114:117], v[198:201], v[102:105]
	ds_read_b128 v[114:117], v190 offset:128
	ds_read_b128 v[206:209], v190 offset:192
	s_waitcnt lgkmcnt(2)
	v_mfma_f32_16x16x32_bf16 v[102:105], v[110:113], v[202:205], v[102:105]
	ds_read_b128 v[110:113], v253 offset:512
	s_waitcnt lgkmcnt(2)
	v_mfma_f32_16x16x32_bf16 v[106:109], v[114:117], v[198:201], v[106:109]
	s_nop 4
	v_sub_f32_e32 v105, v101, v105
	v_sub_f32_e32 v104, v100, v104
	v_sub_f32_e32 v103, v99, v103
	v_sub_f32_e32 v102, v98, v102
	v_cvt_pk_bf16_f32 v114, v102, v103
	s_waitcnt lgkmcnt(0)
	v_pk_mul_f32 v[102:103], v[102:103], v[110:111]
	v_cvt_pk_bf16_f32 v115, v104, v105
	v_pk_mul_f32 v[104:105], v[104:105], v[112:113]
	v_cvt_pk_bf16_f32 v102, v102, v103
	v_cvt_pk_bf16_f32 v103, v104, v105
	ds_write2st64_b64 v194, v[114:115], v[102:103] offset0:112 offset1:121
	ds_read_b128 v[110:113], v253
	v_mfma_f32_16x16x32_bf16 v[114:117], v[206:209], v[202:205], v[106:109]

.Lp4n_cwkeep_A:
	v_lshlrev_b32_e32 v102, 16, v128
	v_and_b32_e32 v103, 0xffff0000, v128
	v_pk_mul_f32 v[102:103], v[94:95], v[102:103]
	v_lshlrev_b32_e32 v104, 16, v129
	v_and_b32_e32 v105, 0xffff0000, v129
	v_pk_mul_f32 v[104:105], v[96:97], v[104:105]
	v_lshlrev_b32_e32 v106, 16, v130
	v_and_b32_e32 v107, 0xffff0000, v130
	v_pk_fma_f32 v[102:103], v[90:91], v[106:107], v[102:103]
	v_lshlrev_b32_e32 v108, 16, v131
	v_and_b32_e32 v109, 0xffff0000, v131
	v_pk_fma_f32 v[104:105], v[92:93], v[108:109], v[104:105]
	v_lshlrev_b32_e32 v106, 16, v132
	v_and_b32_e32 v107, 0xffff0000, v132
	v_pk_fma_f32 v[102:103], v[86:87], v[106:107], v[102:103]
	v_lshlrev_b32_e32 v108, 16, v133
	v_and_b32_e32 v109, 0xffff0000, v133
	v_pk_fma_f32 v[104:105], v[88:89], v[108:109], v[104:105]
	v_lshlrev_b32_e32 v106, 16, v136
	v_and_b32_e32 v107, 0xffff0000, v136
	v_pk_fma_f32 v[102:103], v[82:83], v[106:107], v[102:103]
	v_lshlrev_b32_e32 v108, 16, v137
	v_and_b32_e32 v109, 0xffff0000, v137
	v_pk_fma_f32 v[104:105], v[84:85], v[108:109], v[104:105]
	v_pk_mul_f32 v[106:107], v[102:103], s[100:101] op_sel_hi:[1,0]
	v_pk_mul_f32 v[108:109], v[104:105], s[100:101] op_sel_hi:[1,0]
	v_exp_f32_e32 v106, v106
	v_exp_f32_e32 v107, v107
	v_exp_f32_e32 v108, v108
	v_exp_f32_e32 v109, v109
	v_pk_add_f32 v[106:107], v[106:107], 1.0 op_sel_hi:[1,0]
	v_pk_add_f32 v[108:109], v[108:109], 1.0 op_sel_hi:[1,0]
	v_rcp_f32_e32 v106, v106
	v_rcp_f32_e32 v107, v107
	v_rcp_f32_e32 v108, v108
	v_rcp_f32_e32 v109, v109
	v_pk_mul_f32 v[102:103], v[102:103], v[106:107]
	v_pk_mul_f32 v[104:105], v[104:105], v[108:109]
	s_waitcnt vmcnt(7)
	v_mul_f32_e32 v102, v175, v102
	v_mul_f32_e32 v103, v175, v103
	v_mul_f32_e32 v104, v175, v104
	v_mul_f32_e32 v105, v175, v105
	v_cvt_pk_bf16_f32 v102, v102, s0
	v_cvt_pk_bf16_f32 v103, v103, s0
	v_cvt_pk_bf16_f32 v104, v104, s0
	v_cvt_pk_bf16_f32 v105, v105, s0
	ds_write_b16 v197, v102 offset:26624
	ds_write_b16 v197, v103 offset:26768
	ds_write_b16 v197, v104 offset:26912
	ds_write_b16 v197, v105 offset:27056
	s_and_saveexec_b64 s[8:9], s[4:5]
	s_cbranch_execz .Lp4n_w0done_A
	s_mov_b32 s14, 0x1d900
	s_and_b64 s[20:21], vcc, exec
	s_cselect_b32 s20, 63, 0
	v_and_or_b32 v102, v195, 64, s20
	v_lshlrev_b32_e32 v102, 2, v102
	ds_bpermute_b32 v102, v102, v176
	v_mul_f32_e32 v103, 0x3fb8aa3b, v176
	v_exp_f32_e32 v103, v103
	v_lshl_add_u32 v105, v0, 2, s14
	s_waitcnt lgkmcnt(0)
	v_sub_f32_e32 v104, v102, v176
	v_mul_f32_e32 v104, 0x3fb8aa3b, v104
	v_exp_f32_e32 v104, v104
	v_mul_f32_e32 v106, v177, v103
	ds_write2st64_b32 v105, v103, v106 offset1:1
	ds_write_b32 v105, v104 offset:512
	s_and_b64 exec, exec, s[6:7]
	s_cbranch_execz .Lp4n_w0done_A
	v_mul_f32_e32 v102, 0x3fb8aa3b, v102
	v_exp_f32_e32 v102, v102
	v_mov_b32_e32 v103, s14
	ds_write_b32 v103, v102 offset:768

.Lp4n_nocwn_A:
	s_cmp_lt_u32 s99, 61
	s_cbranch_scc0 .Lp4n_premid_A
	s_add_u32 s46, s99, 3
	s_nop 3
	v_readlane_b32 s8, v221, s46
	v_readlane_b32 s88, v222, s46
	v_readlane_b32 s20, v223, s46
	v_readlane_b32 s47, v224, s46
	v_readlane_b32 s44, v220, s46
	s_add_u32 s88, s72, s88
	s_addc_u32 s89, s73, 0
	s_add_u32 s90, s78, s8
	s_addc_u32 s91, s79, 0
	s_add_u32 s92, s80, s8
	s_addc_u32 s93, s81, 0
	global_load_dwordx4 v[26:29], v239, s[90:91]
	global_load_dwordx4 v[30:33], v240, s[90:91]
	global_load_dwordx4 v[34:37], v241, s[88:89]
	global_load_dwordx4 v[38:41], v242, s[88:89]
	global_load_dwordx4 v[42:45], v239, s[92:93]
	global_load_dwordx4 v[46:49], v240, s[92:93]
	s_ashr_i32 s89, s20, 31
	s_add_u32 s88, s0, s20
	s_addc_u32 s89, s1, s89
	s_bfe_u32 s45, s44, 0x60016
	s_cmp_eq_u32 s45, 0
	s_cbranch_scc1 .Lp4n_vedge_A
	s_bfe_u32 s45, s44, 0x10015
	s_cmp_lg_u32 s45, 0
	s_cbranch_scc1 .Lp4n_vedge_A
	global_load_dwordx2 v[128:129], v120, s[88:89]
	global_load_dwordx2 v[130:131], v247, s[88:89]
	global_load_dwordx2 v[132:133], v248, s[88:89]
	global_load_dwordx2 v[136:137], v249, s[88:89]
	s_branch .Lp4n_vdone_A
.Lp4n_vedge_A:
	v_readlane_b32 s22, v228, s46
	v_readlane_b32 s76, v225, s46
	v_readlane_b32 s77, v226, s46
	v_add_u32_e32 v102, s22, v160
	v_cmp_le_i32_e32 vcc, s76, v102
	v_cmp_gt_i32_e64 s[8:9], s77, v102
	v_mov_b32_e32 v130, v158
	v_mov_b32_e32 v131, v158
	s_and_b64 s[90:91], vcc, s[8:9]
	v_lshl_add_u64 v[102:103], s[88:89], 0, v[120:121]
	v_mov_b64_e32 v[128:129], v[130:131]
	s_and_saveexec_b64 s[8:9], s[90:91]
	s_cbranch_execz .Lp4n_v0_A
	global_load_dwordx2 v[128:129], v[102:103], off

.Lp4n_vdone_A:
	s_add_u32 s8, s30, s47
	s_addc_u32 s9, s31, 0
	global_load_dword v175, v122, s[8:9] offset:512
	s_and_saveexec_b64 s[20:21], s[4:5]
	s_cbranch_execz .Lp4n_gdone_A
	global_load_dword v176, v124, s[8:9]
	global_load_dword v177, v124, s[8:9] offset:512

.Lp4n_premid_A:
.Lp4n_mid_A:
	s_waitcnt lgkmcnt(0)
	s_barrier
	ds_read_b32 v198, v251 offset:768
	ds_read_b128 v[102:105], v196 offset:61952
	ds_read_b128 v[106:109], v196 offset:64256
	s_waitcnt lgkmcnt(2)
	v_pk_mul_f32 v[4:5], v[4:5], v[198:199] op_sel_hi:[1,0]
	v_pk_mul_f32 v[2:3], v[2:3], v[198:199] op_sel_hi:[1,0]
	v_pk_mul_f32 v[8:9], v[8:9], v[198:199] op_sel_hi:[1,0]
	v_pk_mul_f32 v[6:7], v[6:7], v[198:199] op_sel_hi:[1,0]
	s_waitcnt lgkmcnt(1)
	v_mfma_f32_16x16x32_bf16 v[2:5], v[74:77], v[102:105], v[2:5]
	ds_read_b128 v[102:105], v196 offset:62016
	s_waitcnt lgkmcnt(1)
	v_mfma_f32_16x16x32_bf16 v[6:9], v[74:77], v[106:109], v[6:9]
	v_readlane_b32 s8, v227, s99
	s_lshl_b32 s8, s8, 1
	s_add_u32 s8, s0, s8
	s_addc_u32 s9, s1, 0
	s_waitcnt lgkmcnt(0)
	v_mfma_f32_16x16x32_bf16 v[102:105], v[78:81], v[102:105], v[2:5]
	s_nop 2
	ds_read_b128 v[2:5], v196 offset:64320
	ds_read_b128 v[198:201], v191
	ds_read_b128 v[202:205], v187 offset:57344
	s_waitcnt lgkmcnt(2)
	v_mfma_f32_16x16x32_bf16 v[106:109], v[78:81], v[2:5], v[6:9]
	v_mul_f32_e64 v4, v116, v112
	v_mul_f32_e64 v5, v117, v113
	v_pk_mul_f32 v[2:3], v[114:115], v[110:111]
	ds_read_b128 v[110:113], v191 offset:64
	ds_read_b128 v[6:9], v187 offset:57408
	s_waitcnt lgkmcnt(2)
	v_mfma_f32_16x16x32_bf16 v[2:5], v[198:201], v[202:205], v[2:5]
	s_bfe_u32 s45, s41, 0x10015
	s_cmp_eq_u32 s45, 0
	s_waitcnt lgkmcnt(0)
	v_mfma_f32_16x16x32_bf16 v[2:5], v[110:113], v[6:9], v[2:5]
	s_nop 7
	v_cvt_pk_bf16_f32 v2, v2, s0
	global_store_short v243, v2, s[8:9]
	v_cvt_pk_bf16_f32 v8, v3, s0
	global_store_short v244, v8, s[8:9]
	v_cvt_pk_bf16_f32 v4, v4, s0
	global_store_short v245, v4, s[8:9]
	v_cvt_pk_bf16_f32 v3, v5, s0
	global_store_short v246, v3, s[8:9]
	s_cbranch_scc1 .Lp4n_sjoin_A
	s_bfe_u32 s45, s41, 0x10014
	s_cmp_lg_u32 s45, 0
	s_cbranch_scc1 .Lp4n_nosst_A
	s_bfe_u32 s8, s41, 0x5000f
	s_lshl_b32 s8, s8, 4
	s_bfe_u32 s9, s41, 0x1000c
	s_lshl_b32 s9, s9, 3
	s_bfe_u32 s14, s41, 0x30009
	s_add_i32 s8, s14, s8
	s_bfe_u32 s14, s41, 0x2000d
	s_lshl_b32 s14, s14, 5
	s_add_i32 s8, s8, s9
	s_ashr_i32 s9, s8, 31
	s_lshl_b64 s[8:9], s[8:9], 16
	s_add_u32 s20, s72, s8
	s_addc_u32 s21, s73, s9
	s_lshl_b64 s[8:9], s[14:15], 2
	s_add_u32 s8, s20, s8
	s_addc_u32 s9, s21, s9
	v_lshl_add_u64 v[2:3], s[8:9], 0, v[126:127]
	v_lshl_add_u64 v[2:3], v[2:3], 0, s[18:19]
	v_lshl_add_u64 v[4:5], v[2:3], 0, v[144:145]
	v_lshl_add_u64 v[6:7], v[2:3], 0, v[146:147]
	v_lshl_add_u64 v[8:9], v[2:3], 0, v[148:149]
	v_lshl_add_u64 v[2:3], v[2:3], 0, v[150:151]
	global_store_dword v[4:5], v102, off
	global_store_dword v[6:7], v103, off
	global_store_dword v[8:9], v104, off
	global_store_dword v[2:3], v105, off
	global_store_dword v[4:5], v106, off offset:64
	global_store_dword v[6:7], v107, off offset:64
	global_store_dword v[8:9], v108, off offset:64
	global_store_dword v[2:3], v109, off offset:64

.Lp4n_sjoin_A:
	s_nop 0
	v_cvt_pk_bf16_f32 v2, v102, v103
	v_cvt_pk_bf16_f32 v3, v104, v105
	ds_write_b64 v183, v[2:3] offset:48640
	v_cvt_pk_bf16_f32 v2, v106, v107
	v_cvt_pk_bf16_f32 v3, v108, v109
	s_andn2_b64 vcc, exec, s[10:11]
	ds_write_b64 v183, v[2:3] offset:52992
	s_cbranch_vccnz .Lp4n_end_A
	ds_read_b128 v[74:77], v179
	ds_read_b128 v[2:5], v255
	ds_read_b128 v[6:9], v255 offset:16
	ds_read_b128 v[78:81], v179 offset:64
	s_waitcnt lgkmcnt(3)
	v_lshlrev_b32_e32 v98, 16, v74
	v_and_b32_e32 v99, 0xffff0000, v74
	s_waitcnt lgkmcnt(2)
	v_pk_mul_f32 v[2:3], v[2:3], v[98:99]
	v_lshlrev_b32_e32 v98, 16, v75
	v_and_b32_e32 v99, 0xffff0000, v75
	v_pk_mul_f32 v[4:5], v[4:5], v[98:99]
	v_cvt_pk_bf16_f32 v2, v2, v3
	v_cvt_pk_bf16_f32 v3, v4, v5
	v_lshlrev_b32_e32 v4, 16, v76
	v_and_b32_e32 v5, 0xffff0000, v76
	s_waitcnt lgkmcnt(1)
	v_pk_mul_f32 v[4:5], v[6:7], v[4:5]
	v_lshlrev_b32_e32 v6, 16, v77
	v_and_b32_e32 v7, 0xffff0000, v77
	v_pk_mul_f32 v[6:7], v[8:9], v[6:7]
	v_cvt_pk_bf16_f32 v4, v4, v5
	v_cvt_pk_bf16_f32 v5, v6, v7
	ds_read_b128 v[6:9], v196 offset:17408
	ds_read_b128 v[98:101], v196 offset:17472
	ds_read_b128 v[110:113], v196 offset:19712
	ds_read_b128 v[114:117], v196 offset:19776
	ds_read_b128 v[198:201], v196 offset:22016
	ds_read_b128 v[202:205], v196 offset:22080
	ds_read_b128 v[206:209], v196 offset:24320
	ds_read_b128 v[210:213], v255 offset:128
	ds_read_b128 v[214:217], v196 offset:24384
	s_waitcnt lgkmcnt(8)
	v_mfma_f32_16x16x32_bf16 v[6:9], v[2:5], v[6:9], 0
	v_lshlrev_b32_e32 v218, 16, v78
	v_and_b32_e32 v219, 0xffff0000, v78
	s_waitcnt lgkmcnt(1)
	v_pk_mul_f32 v[210:211], v[210:211], v[218:219]
	v_mfma_f32_16x16x32_bf16 v[110:113], v[2:5], v[110:113], 0
	v_lshlrev_b32_e32 v218, 16, v79
	v_and_b32_e32 v219, 0xffff0000, v79
	v_pk_mul_f32 v[212:213], v[212:213], v[218:219]
	v_mfma_f32_16x16x32_bf16 v[198:201], v[2:5], v[198:201], 0
	v_cvt_pk_bf16_f32 v210, v210, v211
	v_cvt_pk_bf16_f32 v211, v212, v213
	v_lshlrev_b32_e32 v212, 16, v80
	v_mfma_f32_16x16x32_bf16 v[2:5], v[2:5], v[206:209], 0
	ds_read_b128 v[206:209], v255 offset:144
	v_and_b32_e32 v213, 0xffff0000, v80
	s_waitcnt lgkmcnt(0)
	v_pk_mul_f32 v[206:207], v[206:207], v[212:213]
	s_nop 0
	v_cvt_pk_bf16_f32 v212, v206, v207
	v_lshlrev_b32_e32 v206, 16, v81
	v_and_b32_e32 v207, 0xffff0000, v81
	v_pk_mul_f32 v[206:207], v[208:209], v[206:207]
	s_nop 0
	v_cvt_pk_bf16_f32 v213, v206, v207
	s_nop 1
	v_mfma_f32_16x16x32_bf16 v[6:9], v[210:213], v[98:101], v[6:9]
	v_mfma_f32_16x16x32_bf16 v[98:101], v[210:213], v[114:117], v[110:113]
	s_nop 6
	v_cvt_pk_bf16_f32 v6, v6, v7
	v_cvt_pk_bf16_f32 v7, v8, v9
	ds_write_b64 v183, v[6:7] offset:31232
	v_mfma_f32_16x16x32_bf16 v[110:113], v[210:213], v[202:205], v[198:201]
	v_add_u32_e32 v8, v174, v188
	v_cvt_pk_bf16_f32 v6, v98, v99
	v_cvt_pk_bf16_f32 v7, v100, v101
	v_mfma_f32_16x16x32_bf16 v[2:5], v[210:213], v[214:217], v[2:5]
	ds_write_b64 v183, v[6:7] offset:35584
	s_nop 2
	v_cvt_pk_bf16_f32 v6, v110, v111
	v_cvt_pk_bf16_f32 v7, v112, v113
	ds_write_b64 v8, v[6:7] offset:31232
	s_nop 0
	v_cvt_pk_bf16_f32 v2, v2, v3
	v_cvt_pk_bf16_f32 v3, v4, v5
	ds_write_b64 v8, v[2:3] offset:35584
	ds_read_b128 v[2:5], v186 offset:17408
	ds_read_b128 v[6:9], v186 offset:17472
	ds_read_b128 v[98:101], v187 offset:26624
	ds_read_b128 v[110:113], v187 offset:26688
	s_waitcnt lgkmcnt(1)
	v_mfma_f32_16x16x32_bf16 v[2:5], v[2:5], v[98:101], 0
	s_waitcnt lgkmcnt(0)
	v_mfma_f32_16x16x32_bf16 v[98:101], v[6:9], v[110:113], v[2:5]

.Lp4n_top_B:
	s_cmp_lt_u32 s99, 63
	s_cselect_b64 s[10:11], -1, 0
	ds_read_b128 v[2:5], v193 offset:31232
	ds_read_b128 v[6:9], v192 offset:48640
	ds_read_b128 v[110:113], v192 offset:48704
	ds_read_b128 v[114:117], v193 offset:31296
	ds_read_b128 v[198:201], v190 offset:17408
	ds_read_b128 v[202:205], v190 offset:17472
	s_waitcnt lgkmcnt(0)
	v_mfma_f32_16x16x32_bf16 v[2:5], v[2:5], v[6:9], 0
	s_waitcnt lgkmcnt(1)
	v_mfma_f32_16x16x32_bf16 v[6:9], v[198:201], v[6:9], 0
	v_mfma_f32_16x16x32_bf16 v[2:5], v[114:117], v[110:113], v[2:5]
	ds_read_b128 v[114:117], v193 offset:31360
	ds_read_b128 v[198:201], v192 offset:48768
	s_waitcnt lgkmcnt(2)
	v_mfma_f32_16x16x32_bf16 v[6:9], v[202:205], v[110:113], v[6:9]
	ds_read_b128 v[110:113], v193 offset:31424
	ds_read_b128 v[202:205], v192 offset:48832
	s_waitcnt lgkmcnt(2)
	v_mfma_f32_16x16x32_bf16 v[2:5], v[114:117], v[198:201], v[2:5]
	ds_read_b128 v[114:117], v190 offset:17536
	ds_read_b128 v[206:209], v190 offset:17600
	s_waitcnt lgkmcnt(2)
	v_mfma_f32_16x16x32_bf16 v[2:5], v[110:113], v[202:205], v[2:5]
	ds_read_b128 v[110:113], v254 offset:512
	s_waitcnt lgkmcnt(2)
	v_mfma_f32_16x16x32_bf16 v[6:9], v[114:117], v[198:201], v[6:9]
	s_nop 4
	v_sub_f32_e32 v5, v101, v5
	v_sub_f32_e32 v4, v100, v4
	v_sub_f32_e32 v3, v99, v3
	v_sub_f32_e32 v2, v98, v2
	v_cvt_pk_bf16_f32 v114, v2, v3
	s_waitcnt lgkmcnt(0)
	v_pk_mul_f32 v[2:3], v[2:3], v[110:111]
	v_cvt_pk_bf16_f32 v115, v4, v5
	v_pk_mul_f32 v[4:5], v[4:5], v[112:113]
	v_cvt_pk_bf16_f32 v2, v2, v3
	v_cvt_pk_bf16_f32 v3, v4, v5
	ds_write2st64_b64 v194, v[114:115], v[2:3] offset0:112 offset1:121
	ds_read_b128 v[110:113], v254
	v_mfma_f32_16x16x32_bf16 v[114:117], v[206:209], v[202:205], v[6:9]

.Lp4n_cwkeep_B:
	v_lshlrev_b32_e32 v2, 16, v134
	v_and_b32_e32 v3, 0xffff0000, v134
	v_pk_mul_f32 v[2:3], v[94:95], v[2:3]
	v_lshlrev_b32_e32 v4, 16, v135
	v_and_b32_e32 v5, 0xffff0000, v135
	v_pk_mul_f32 v[4:5], v[96:97], v[4:5]
	v_lshlrev_b32_e32 v6, 16, v138
	v_and_b32_e32 v7, 0xffff0000, v138
	v_pk_fma_f32 v[2:3], v[90:91], v[6:7], v[2:3]
	v_lshlrev_b32_e32 v8, 16, v139
	v_and_b32_e32 v9, 0xffff0000, v139
	v_pk_fma_f32 v[4:5], v[92:93], v[8:9], v[4:5]
	v_lshlrev_b32_e32 v6, 16, v140
	v_and_b32_e32 v7, 0xffff0000, v140
	v_pk_fma_f32 v[2:3], v[86:87], v[6:7], v[2:3]
	v_lshlrev_b32_e32 v8, 16, v141
	v_and_b32_e32 v9, 0xffff0000, v141
	v_pk_fma_f32 v[4:5], v[88:89], v[8:9], v[4:5]
	v_lshlrev_b32_e32 v6, 16, v142
	v_and_b32_e32 v7, 0xffff0000, v142
	v_pk_fma_f32 v[2:3], v[82:83], v[6:7], v[2:3]
	v_lshlrev_b32_e32 v8, 16, v143
	v_and_b32_e32 v9, 0xffff0000, v143
	v_pk_fma_f32 v[4:5], v[84:85], v[8:9], v[4:5]
	v_pk_mul_f32 v[6:7], v[2:3], s[100:101] op_sel_hi:[1,0]
	v_pk_mul_f32 v[8:9], v[4:5], s[100:101] op_sel_hi:[1,0]
	v_exp_f32_e32 v6, v6
	v_exp_f32_e32 v7, v7
	v_exp_f32_e32 v8, v8
	v_exp_f32_e32 v9, v9
	v_pk_add_f32 v[6:7], v[6:7], 1.0 op_sel_hi:[1,0]
	v_pk_add_f32 v[8:9], v[8:9], 1.0 op_sel_hi:[1,0]
	v_rcp_f32_e32 v6, v6
	v_rcp_f32_e32 v7, v7
	v_rcp_f32_e32 v8, v8
	v_rcp_f32_e32 v9, v9
	v_pk_mul_f32 v[2:3], v[2:3], v[6:7]
	v_pk_mul_f32 v[4:5], v[4:5], v[8:9]
	s_waitcnt vmcnt(7)
	v_mul_f32_e32 v2, v181, v2
	v_mul_f32_e32 v3, v181, v3
	v_mul_f32_e32 v4, v181, v4
	v_mul_f32_e32 v5, v181, v5
	v_cvt_pk_bf16_f32 v2, v2, s0
	v_cvt_pk_bf16_f32 v3, v3, s0
	v_cvt_pk_bf16_f32 v4, v4, s0
	v_cvt_pk_bf16_f32 v5, v5, s0
	ds_write_b16 v197, v2 offset:26624
	ds_write_b16 v197, v3 offset:26768
	ds_write_b16 v197, v4 offset:26912
	ds_write_b16 v197, v5 offset:27056
	s_and_saveexec_b64 s[8:9], s[4:5]
	s_cbranch_execz .Lp4n_w0done_B
	s_mov_b32 s14, 0x1d400
	s_and_b64 s[20:21], vcc, exec
	s_cselect_b32 s20, 63, 0
	v_and_or_b32 v2, v195, 64, s20
	v_lshlrev_b32_e32 v2, 2, v2
	ds_bpermute_b32 v2, v2, v184
	v_mul_f32_e32 v3, 0x3fb8aa3b, v184
	v_exp_f32_e32 v3, v3
	v_lshl_add_u32 v5, v0, 2, s14
	s_waitcnt lgkmcnt(0)
	v_sub_f32_e32 v4, v2, v184
	v_mul_f32_e32 v4, 0x3fb8aa3b, v4
	v_exp_f32_e32 v4, v4
	v_mul_f32_e32 v6, v185, v3
	ds_write2st64_b32 v5, v3, v6 offset1:1
	ds_write_b32 v5, v4 offset:512
	s_and_b64 exec, exec, s[6:7]
	s_cbranch_execz .Lp4n_w0done_B
	v_mul_f32_e32 v2, 0x3fb8aa3b, v2
	v_exp_f32_e32 v2, v2
	v_mov_b32_e32 v3, s14
	ds_write_b32 v3, v2 offset:768

.Lp4n_nocwn_B:
	s_cmp_lt_u32 s99, 61
	s_cbranch_scc0 .Lp4n_premid_B
	s_add_u32 s46, s99, 3
	s_nop 3
	v_readlane_b32 s8, v221, s46
	v_readlane_b32 s88, v222, s46
	v_readlane_b32 s20, v223, s46
	v_readlane_b32 s47, v224, s46
	v_readlane_b32 s44, v220, s46
	s_add_u32 s88, s72, s88
	s_addc_u32 s89, s73, 0
	s_add_u32 s90, s78, s8
	s_addc_u32 s91, s79, 0
	s_add_u32 s92, s80, s8
	s_addc_u32 s93, s81, 0
	global_load_dwordx4 v[50:53], v239, s[90:91]
	global_load_dwordx4 v[54:57], v240, s[90:91]
	global_load_dwordx4 v[58:61], v241, s[88:89]
	global_load_dwordx4 v[62:65], v242, s[88:89]
	global_load_dwordx4 v[66:69], v239, s[92:93]
	global_load_dwordx4 v[70:73], v240, s[92:93]
	s_ashr_i32 s89, s20, 31
	s_add_u32 s88, s0, s20
	s_addc_u32 s89, s1, s89
	s_bfe_u32 s45, s44, 0x60016
	s_cmp_eq_u32 s45, 0
	s_cbranch_scc1 .Lp4n_vedge_B
	s_bfe_u32 s45, s44, 0x10015
	s_cmp_lg_u32 s45, 0
	s_cbranch_scc1 .Lp4n_vedge_B
	global_load_dwordx2 v[134:135], v120, s[88:89]
	global_load_dwordx2 v[138:139], v247, s[88:89]
	global_load_dwordx2 v[140:141], v248, s[88:89]
	global_load_dwordx2 v[142:143], v249, s[88:89]
	s_branch .Lp4n_vdone_B
.Lp4n_vedge_B:
	v_readlane_b32 s22, v228, s46
	v_readlane_b32 s76, v225, s46
	v_readlane_b32 s77, v226, s46
	v_add_u32_e32 v2, s22, v160
	v_cmp_le_i32_e32 vcc, s76, v2
	v_cmp_gt_i32_e64 s[8:9], s77, v2
	v_mov_b32_e32 v138, v158
	v_mov_b32_e32 v139, v158
	s_and_b64 s[90:91], vcc, s[8:9]
	v_lshl_add_u64 v[2:3], s[88:89], 0, v[120:121]
	v_mov_b64_e32 v[134:135], v[138:139]
	s_and_saveexec_b64 s[8:9], s[90:91]
	s_cbranch_execz .Lp4n_v0_B
	global_load_dwordx2 v[134:135], v[2:3], off

.Lp4n_vdone_B:
	s_add_u32 s8, s30, s47
	s_addc_u32 s9, s31, 0
	global_load_dword v181, v122, s[8:9] offset:512
	s_and_saveexec_b64 s[20:21], s[4:5]
	s_cbranch_execz .Lp4n_gdone_B
	global_load_dword v184, v124, s[8:9]
	global_load_dword v185, v124, s[8:9] offset:512

.Lp4n_premid_B:
.Lp4n_mid_B:
	s_waitcnt lgkmcnt(0)
	s_barrier
	ds_read_b32 v198, v252 offset:768
	ds_read_b128 v[2:5], v196 offset:61952
	ds_read_b128 v[6:9], v196 offset:64256
	s_waitcnt lgkmcnt(2)
	v_pk_mul_f32 v[104:105], v[104:105], v[198:199] op_sel_hi:[1,0]
	v_pk_mul_f32 v[102:103], v[102:103], v[198:199] op_sel_hi:[1,0]
	v_pk_mul_f32 v[108:109], v[108:109], v[198:199] op_sel_hi:[1,0]
	v_pk_mul_f32 v[106:107], v[106:107], v[198:199] op_sel_hi:[1,0]
	s_waitcnt lgkmcnt(1)
	v_mfma_f32_16x16x32_bf16 v[102:105], v[74:77], v[2:5], v[102:105]
	ds_read_b128 v[2:5], v196 offset:62016
	s_waitcnt lgkmcnt(1)
	v_mfma_f32_16x16x32_bf16 v[106:109], v[74:77], v[6:9], v[106:109]
	v_readlane_b32 s8, v227, s99
	s_lshl_b32 s8, s8, 1
	s_add_u32 s8, s0, s8
	s_addc_u32 s9, s1, 0
	s_waitcnt lgkmcnt(0)
	v_mfma_f32_16x16x32_bf16 v[2:5], v[78:81], v[2:5], v[102:105]
	s_nop 2
	ds_read_b128 v[102:105], v196 offset:64320
	ds_read_b128 v[198:201], v191 offset:9216
	ds_read_b128 v[202:205], v187 offset:57344
	s_waitcnt lgkmcnt(2)
	v_mfma_f32_16x16x32_bf16 v[6:9], v[78:81], v[102:105], v[106:109]
	v_mul_f32_e64 v104, v116, v112
	v_mul_f32_e64 v105, v117, v113
	v_pk_mul_f32 v[102:103], v[114:115], v[110:111]
	ds_read_b128 v[110:113], v191 offset:9280
	ds_read_b128 v[106:109], v187 offset:57408
	s_waitcnt lgkmcnt(2)
	v_mfma_f32_16x16x32_bf16 v[102:105], v[198:201], v[202:205], v[102:105]
	s_bfe_u32 s45, s41, 0x10015
	s_cmp_eq_u32 s45, 0
	s_waitcnt lgkmcnt(0)
	v_mfma_f32_16x16x32_bf16 v[102:105], v[110:113], v[106:109], v[102:105]
	s_nop 7
	v_cvt_pk_bf16_f32 v102, v102, s0
	global_store_short v243, v102, s[8:9]
	v_cvt_pk_bf16_f32 v108, v103, s0
	global_store_short v244, v108, s[8:9]
	v_cvt_pk_bf16_f32 v104, v104, s0
	global_store_short v245, v104, s[8:9]
	v_cvt_pk_bf16_f32 v103, v105, s0
	global_store_short v246, v103, s[8:9]
	s_cbranch_scc1 .Lp4n_sjoin_B
	s_bfe_u32 s45, s41, 0x10014
	s_cmp_lg_u32 s45, 0
	s_cbranch_scc1 .Lp4n_nosst_B
	s_bfe_u32 s8, s41, 0x5000f
	s_lshl_b32 s8, s8, 4
	s_bfe_u32 s9, s41, 0x1000c
	s_lshl_b32 s9, s9, 3
	s_bfe_u32 s14, s41, 0x30009
	s_add_i32 s8, s14, s8
	s_bfe_u32 s14, s41, 0x2000d
	s_lshl_b32 s14, s14, 5
	s_add_i32 s8, s8, s9
	s_ashr_i32 s9, s8, 31
	s_lshl_b64 s[8:9], s[8:9], 16
	s_add_u32 s20, s72, s8
	s_addc_u32 s21, s73, s9
	s_lshl_b64 s[8:9], s[14:15], 2
	s_add_u32 s8, s20, s8
	s_addc_u32 s9, s21, s9
	v_lshl_add_u64 v[102:103], s[8:9], 0, v[126:127]
	v_lshl_add_u64 v[102:103], v[102:103], 0, s[18:19]
	v_lshl_add_u64 v[104:105], v[102:103], 0, v[144:145]
	v_lshl_add_u64 v[106:107], v[102:103], 0, v[146:147]
	v_lshl_add_u64 v[108:109], v[102:103], 0, v[148:149]
	v_lshl_add_u64 v[102:103], v[102:103], 0, v[150:151]
	global_store_dword v[104:105], v2, off
	global_store_dword v[106:107], v3, off
	global_store_dword v[108:109], v4, off
	global_store_dword v[102:103], v5, off
	global_store_dword v[104:105], v6, off offset:64
	global_store_dword v[106:107], v7, off offset:64
	global_store_dword v[108:109], v8, off offset:64
	global_store_dword v[102:103], v9, off offset:64
